# out/ffn-down sample-row GEMM: split-K LDS reduction reads and residual loads issued together, counted waits
# speedup vs baseline: 1.0038x; 1.0038x over previous
.LBB0_392:
	v_add_u32_e32 v0, s19, v17
	s_andn2_b64 vcc, exec, s[12:13]
	s_nop 0
	ds_write_b128 v0, v[6:9]
	s_nop 2
	ds_write_b128 v0, v[10:13] offset:1024
	s_waitcnt lgkmcnt(0)
	s_barrier
	s_cbranch_vccnz .LBB0_386
	v_lshlrev_b32_e32 v0, 10, v30
	s_ashr_i32 s15, s14, 31
	v_lshl_add_u64 v[36:37], v[0:1], 0, s[14:15]
	v_or_b32_e32 v36, v36, v16
	v_lshlrev_b64 v[38:39], 2, v[36:37]
	v_lshl_add_u64 v[40:41], s[2:3], 0, v[38:39]
	ds_read_b128 v[64:67], v17 offset:2048
	ds_read_b128 v[68:71], v17 offset:3072
	ds_read_b128 v[72:75], v17 offset:4096
	ds_read_b128 v[76:79], v17 offset:5120
	ds_read_b128 v[80:83], v17 offset:6144
	ds_read_b128 v[84:87], v17 offset:7168
	ds_read_b128 v[88:91], v17 offset:8192
	ds_read_b128 v[92:95], v17 offset:9216
	ds_read_b128 v[96:99], v17 offset:10240
	ds_read_b128 v[100:103], v17 offset:11264
	ds_read_b128 v[104:107], v17 offset:12288
	ds_read_b128 v[108:111], v17 offset:13312
	ds_read_b128 v[112:115], v17 offset:14336
	ds_read_b128 v[116:119], v17 offset:15360
	global_load_dwordx4 v[120:123], v[40:41], off
	global_load_dwordx4 v[124:127], v[40:41], off offset:64
	s_waitcnt lgkmcnt(13)
	v_pk_add_f32 v[24:25], v[8:9], v[66:67]
	v_pk_add_f32 v[22:23], v[6:7], v[64:65]
	s_waitcnt lgkmcnt(12)
	v_pk_add_f32 v[12:13], v[12:13], v[70:71]
	v_pk_add_f32 v[10:11], v[10:11], v[68:69]
	s_waitcnt lgkmcnt(11)
	v_pk_add_f32 v[24:25], v[24:25], v[74:75]
	v_pk_add_f32 v[22:23], v[22:23], v[72:73]
	s_waitcnt lgkmcnt(10)
	v_pk_add_f32 v[12:13], v[12:13], v[78:79]
	v_pk_add_f32 v[10:11], v[10:11], v[76:77]
	s_waitcnt lgkmcnt(9)
	v_pk_add_f32 v[24:25], v[24:25], v[82:83]
	v_pk_add_f32 v[22:23], v[22:23], v[80:81]
	s_waitcnt lgkmcnt(8)
	v_pk_add_f32 v[12:13], v[12:13], v[86:87]
	v_pk_add_f32 v[10:11], v[10:11], v[84:85]
	s_waitcnt lgkmcnt(7)
	v_pk_add_f32 v[24:25], v[24:25], v[90:91]
	v_pk_add_f32 v[22:23], v[22:23], v[88:89]
	s_waitcnt lgkmcnt(6)
	v_pk_add_f32 v[12:13], v[12:13], v[94:95]
	v_pk_add_f32 v[10:11], v[10:11], v[92:93]
	s_waitcnt lgkmcnt(5)
	v_pk_add_f32 v[24:25], v[24:25], v[98:99]
	v_pk_add_f32 v[22:23], v[22:23], v[96:97]
	s_waitcnt lgkmcnt(4)
	v_pk_add_f32 v[12:13], v[12:13], v[102:103]
	v_pk_add_f32 v[10:11], v[10:11], v[100:101]
	s_waitcnt lgkmcnt(3)
	v_pk_add_f32 v[24:25], v[24:25], v[106:107]
	v_pk_add_f32 v[22:23], v[22:23], v[104:105]
	s_waitcnt lgkmcnt(2)
	v_pk_add_f32 v[12:13], v[12:13], v[110:111]
	v_pk_add_f32 v[10:11], v[10:11], v[108:109]
	s_waitcnt lgkmcnt(1)
	v_pk_add_f32 v[24:25], v[24:25], v[114:115]
	v_pk_add_f32 v[26:27], v[22:23], v[112:113]
	s_waitcnt lgkmcnt(0)
	v_pk_add_f32 v[32:33], v[12:13], v[118:119]
	v_pk_add_f32 v[34:35], v[10:11], v[116:117]
	v_or_b32_e32 v22, 16, v36
	v_mov_b32_e32 v23, v37
	s_waitcnt vmcnt(1)
	v_pk_add_f32 v[12:13], v[24:25], v[122:123]
	v_pk_add_f32 v[10:11], v[26:27], v[120:121]
	v_lshl_add_u64 v[24:25], s[6:7], 0, v[38:39]
	global_store_dwordx4 v[24:25], v[10:13], off
	v_lshl_add_u64 v[24:25], v[22:23], 2, s[6:7]
	v_and_b32_sdwa v26, v11, v218 dst_sel:DWORD dst_unused:UNUSED_PAD src0_sel:WORD_1 src1_sel:DWORD
	v_and_b32_sdwa v0, v12, v218 dst_sel:DWORD dst_unused:UNUSED_PAD src0_sel:WORD_1 src1_sel:DWORD
	v_add3_u32 v26, v11, v26, s91
	v_add3_u32 v0, v12, v0, s91
	v_and_b32_e32 v26, 0xffff0000, v26
	v_lshl_add_u64 v[22:23], v[22:23], 1, s[8:9]
	s_waitcnt vmcnt(1)
	v_pk_add_f32 v[8:9], v[32:33], v[126:127]
	v_pk_add_f32 v[6:7], v[34:35], v[124:125]
	global_store_dwordx4 v[24:25], v[6:9], off
	v_and_b32_sdwa v25, v13, v218 dst_sel:DWORD dst_unused:UNUSED_PAD src0_sel:WORD_1 src1_sel:DWORD
	v_and_b32_sdwa v24, v10, v218 dst_sel:DWORD dst_unused:UNUSED_PAD src0_sel:WORD_1 src1_sel:DWORD
	v_add3_u32 v25, v13, v25, s91
	v_add3_u32 v24, v10, v24, s91
	v_and_b32_e32 v25, 0xffff0000, v25
	v_or_b32_sdwa v25, v25, v0 dst_sel:DWORD dst_unused:UNUSED_PAD src0_sel:DWORD src1_sel:WORD_1
	v_or_b32_sdwa v24, v26, v24 dst_sel:DWORD dst_unused:UNUSED_PAD src0_sel:DWORD src1_sel:WORD_1
	v_lshl_add_u64 v[26:27], v[36:37], 1, s[8:9]
	global_store_dwordx2 v[26:27], v[24:25], off
	v_and_b32_sdwa v25, v9, v218 dst_sel:DWORD dst_unused:UNUSED_PAD src0_sel:WORD_1 src1_sel:DWORD
	v_and_b32_sdwa v0, v8, v218 dst_sel:DWORD dst_unused:UNUSED_PAD src0_sel:WORD_1 src1_sel:DWORD
	v_add3_u32 v25, v9, v25, s91
	v_add3_u32 v0, v8, v0, s91
	v_and_b32_sdwa v26, v7, v218 dst_sel:DWORD dst_unused:UNUSED_PAD src0_sel:WORD_1 src1_sel:DWORD
	v_and_b32_e32 v25, 0xffff0000, v25
	v_and_b32_sdwa v24, v6, v218 dst_sel:DWORD dst_unused:UNUSED_PAD src0_sel:WORD_1 src1_sel:DWORD
	v_add3_u32 v26, v7, v26, s91
	v_or_b32_sdwa v25, v25, v0 dst_sel:DWORD dst_unused:UNUSED_PAD src0_sel:DWORD src1_sel:WORD_1
	v_mul_f32_e32 v0, v11, v11
	v_mul_f32_e32 v7, v7, v7
	v_add3_u32 v24, v6, v24, s91
	v_fmac_f32_e32 v0, v10, v10
	v_mul_f32_e32 v10, v13, v13
	v_fmac_f32_e32 v7, v6, v6
	v_mul_f32_e32 v6, v9, v9
	v_fmac_f32_e32 v10, v12, v12
	v_fmac_f32_e32 v6, v8, v8
	v_add_f32_e32 v0, v0, v10
	v_add_f32_e32 v6, v7, v6
	v_add_f32_e32 v0, v0, v6
	ds_bpermute_b32 v6, v28, v0
	v_and_b32_e32 v26, 0xffff0000, v26
	v_or_b32_sdwa v24, v26, v24 dst_sel:DWORD dst_unused:UNUSED_PAD src0_sel:DWORD src1_sel:WORD_1
	global_store_dwordx2 v[22:23], v[24:25], off
	s_waitcnt lgkmcnt(0)
	v_add_f32_e32 v0, v0, v6
	ds_bpermute_b32 v6, v29, v0
	s_and_saveexec_b64 s[14:15], s[4:5]
	s_cbranch_execz .LBB0_385
	s_ashr_i32 s16, s23, 3
	v_lshl_add_u32 v8, v30, 5, s16
	v_ashrrev_i32_e32 v9, 31, v8
	v_lshl_add_u64 v[8:9], v[8:9], 2, s[10:11]
	s_waitcnt lgkmcnt(0)
	v_add_f32_e32 v0, v0, v6
	global_store_dword v[8:9], v0, off
	s_branch .LBB0_385
